# attention loops prefetch the next unit's queue index during the current unit; permlane swap scratch moved to the dead bpermute address register
# baseline (speedup 1.0000x reference)
; #define GROUP_LOOP(qi, total, ...) for (int gi_ = 0;; ++gi_) { if (threadIdx.x == 0) ctlw[22 + (gi_ & 1)] = __hip_atomic_fetch_add(qbase + 64 * (qi), 1u, __ATOMIC_RELAXED, __HIP_MEMORY_SCOPE_AGENT); \
;         group_bar(gb, lane); const int u = (int)ctlw[22 + (gi_ & 1)]; if (u >= (total)) break; __VA_ARGS__ }
; template <int MASK> __device__ __forceinline__ void phase3(const Params& p, LAS unsigned char* lds, volatile LAS unsigned* ctlw, int qset) {
;     ...
;     const unsigned gb0 = __builtin_amdgcn_readfirstlane(ctlw[20]);
;     __syncthreads();
;     {
;         int tid = threadIdx.x; asm volatile("" : "+v"(tid));
;         const int wid = __builtin_amdgcn_readfirstlane(tid >> 6), lane = tid & 63;
;         if (wid < 4) {
;             GroupBar gb; gb.cnt = ctlw + 20; gb.gen = gb0;
;             __builtin_amdgcn_s_setprio(1);
;             GROUP_LOOP(2, U_SB, {
.LBB0_835:
	s_add_i32 s53, 0, 0x27e50
	v_mov_b32_e32 v1, s53
	ds_read_b32 v1, v1
	v_mov_b32_e32 v193, v0
	s_waitcnt lgkmcnt(0)
	s_barrier
	s_mov_b32 s45, 0
	v_readfirstlane_b32 s2, v193
	s_ashr_i32 s24, s2, 6
	v_and_b32_e32 v169, 63, v193
	v_readfirstlane_b32 s54, v1
	s_cmp_gt_i32 s24, 3
	v_cmp_eq_u32_e64 s[2:3], 0, v169
	s_cbranch_scc1 .LBB0_961
	s_add_u32 s33, s90, 0xe000000
	s_addc_u32 s52, s91, 0
	s_setprio 1
	v_mov_b32_e32 v3, 0
	v_mov_b32_e32 v194, s53
	s_movk_i32 s55, 0x3600
	s_movk_i32 s62, 0x70
	s_mov_b32 s63, 0xfffff0
	s_movk_i32 s64, 0xc0
	s_movk_i32 s65, 0x60
	s_movk_i32 s66, 0x80
	s_movk_i32 s67, 0xa0
	s_movk_i32 s70, 0xe0
	s_movk_i32 s71, 0x118
	s_and_saveexec_b64 s[4:5], s[0:1]
	s_cbranch_execz .Lpf_sb0
	v_mov_b32_e32 v255, 1
	global_atomic_add v255, v3, v255, s[90:91] offset:768 sc0
.Lpf_sb0:
	s_or_b64 exec, exec, s[4:5]
	s_mov_b32 s72, 0
	s_branch .LBB0_839

.LBB0_842:
	s_or_b64 exec, exec, s[6:7]
	s_and_b32 s6, s72, 1
	s_lshl_b32 s6, s6, 2
	s_add_i32 s6, s6, 0
	s_waitcnt vmcnt(0)
	v_mov_b32_e32 v2, v255
	s_nop 0
	v_readfirstlane_b32 s7, v2
	s_add_i32 s6, s6, 0x27e58
	v_mov_b32_e32 v2, s6
	v_add_u32_e32 v1, s7, v1
	ds_write_b32 v2, v1

; #define LAS __attribute__((address_space(3)))
; #define GROUP_LOOP(qi, total, ...) for (int gi_ = 0;; ++gi_) { if (threadIdx.x == 0) ctlw[22 + (gi_ & 1)] = __hip_atomic_fetch_add(qbase + 64 * (qi), 1u, __ATOMIC_RELAXED, __HIP_MEMORY_SCOPE_AGENT); \
;         group_bar(gb, lane); const int u = (int)ctlw[22 + (gi_ & 1)]; if (u >= (total)) break; __VA_ARGS__ }
; template <int MODE> ...
;     ...
;     int tid = threadIdx.x; asm volatile("" : "+v"(tid));
;     const int wid = __builtin_amdgcn_readfirstlane(tid >> 6), lane = tid & 63, r32 = lane & 31, hi = lane >> 5;
;     constexpr int SHM_V = 16384, SHM_K = 16384;
;     LAS unsigned char* V_lds = lds; LAS unsigned char* K_lds = lds + 2 * SHM_V;
;     LAS float* wsf = (LAS float*)(lds + 73728) + wid * 64;
;     f32x16 o[4];
; #pragma unroll
;     for (int d = 0; d < 4; ++d) o[d] = f32x16{};
;     bf16x8 qr[8];
;     { int qrow = wid * 32 + r32; qrow = qrow < a.nvalid ? qrow : a.nvalid - 1;
;       const bf16_t* Qw = a.Q + (size_t)qrow * a.qstride + hi * 8;
; #pragma unroll
;       for (int d0 = 0; d0 < 8; ++d0) qr[d0] = *(const bf16x8*)(Qw + d0 * 16); }
; template <int MASK> __device__ __forceinline__ void phase3(const Params& p, LAS unsigned char* lds, volatile LAS unsigned* ctlw, int qset) {
;     ...
;             GROUP_LOOP(2, U_SB, {
;                 const int i = 15 - (u >> 5), bh = u & 31, b = bh >> 3, h = bh & 7;
;                 attn_unit<0>(lds, gb, PROJ + (size_t)(b * SEQ + i * 128) * NPAD + PC_Q + h * 128, NPAD,
;                              PROJ + (size_t)(b * SEQ) * NPAD + PC_K + h * 128, PROJ + (size_t)(b * SEQ) * NPAD + PC_V + h * 128, NPAD,
;                              2 * (i + 1), i * 128, 128, p.in[I_SBBIAS][h] * LOG2E,
;                              PROJ + (size_t)(b * SEQ + i * 128) * NPAD + PC_GSB + h * 128, NPAD, MIX + (size_t)(b * SEQ + i * 128) * 2048 + 512 + h * 128, 2048); })
.LBB0_848:
	s_and_b32 s4, s72, 1
	s_lshl_b32 s4, s4, 2
	s_add_i32 s4, s4, 0
	s_add_i32 s4, s4, 0x27e58
	v_mov_b32_e32 v1, s4
	ds_read_b32 v1, v1
	s_movk_i32 s4, 0x200
	s_waitcnt lgkmcnt(0)
	v_cmp_gt_i32_e32 vcc, s4, v1
	v_readfirstlane_b32 s6, v1
	s_mov_b64 s[4:5], -1
	s_cbranch_vccz .LBB0_838
	s_and_saveexec_b64 s[8:9], s[0:1]
	s_cbranch_execz .Lpf_sb1
	v_mov_b32_e32 v255, 1
	global_atomic_add v255, v3, v255, s[90:91] offset:768 sc0
.Lpf_sb1:
	s_or_b64 exec, exec, s[8:9]
	s_ashr_i32 s10, s6, 5
	s_lshl_b32 s4, s6, 8
	s_and_b32 s12, s4, 0x1800
	s_lshl_b32 s4, s10, 7
	s_sub_i32 s78, 0x780, s4
	s_add_i32 s44, s78, s12
	s_and_b32 s11, s6, 7
	s_mul_i32 s5, s44, 0x3600
	s_mul_hi_u32 s4, s44, 0x3600
	s_add_u32 s74, s48, s5
	s_addc_u32 s75, s49, s4
	s_lshl_b32 s4, s11, 8
	s_add_u32 s4, s74, s4
	s_addc_u32 s5, s75, 0
	s_lshl_b32 s6, s11, 2
	v_mov_b32_e32 v1, s6
	v_mov_b32_e32 v195, v0
	global_load_dword v1, v1, s[80:81]
	v_mov_b64_e32 v[4:5], s[4:5]
	v_readfirstlane_b32 s6, v195
	s_ashr_i32 s79, s6, 6
	v_and_b32_e32 v197, 31, v195
	s_lshl_b32 s76, s79, 5
	v_or_b32_e32 v2, s76, v197
	v_bfe_u32 v198, v195, 5, 1
	v_min_i32_e32 v2, 0x7f, v2
	v_mad_i64_i32 v[6:7], s[4:5], v2, s55, v[4:5]
	v_lshlrev_b32_e32 v4, 4, v198
	v_mov_b32_e32 v5, v3
	v_lshl_add_u64 v[6:7], v[6:7], 0, v[4:5]
	global_load_dwordx4 v[100:103], v[6:7], off
	global_load_dwordx4 v[104:107], v[6:7], off offset:32
	global_load_dwordx4 v[108:111], v[6:7], off offset:64
	global_load_dwordx4 v[112:115], v[6:7], off offset:96
	global_load_dwordx4 v[116:119], v[6:7], off offset:128
	global_load_dwordx4 v[120:123], v[6:7], off offset:160
	global_load_dwordx4 v[124:127], v[6:7], off offset:192
	global_load_dwordx4 v[128:131], v[6:7], off offset:224
	s_waitcnt lgkmcnt(0)
	v_and_b32_e32 v196, 63, v195
	v_cmp_eq_u32_e64 s[4:5], 0, v196
	s_and_saveexec_b64 s[6:7], s[4:5]
	s_cbranch_execz .LBB0_852
	s_mov_b64 s[8:9], exec
	v_mbcnt_lo_u32_b32 v2, s8, 0
	v_mbcnt_hi_u32_b32 v2, s9, v2
	v_cmp_eq_u32_e32 vcc, 0, v2
	s_and_b64 s[14:15], exec, vcc
	s_mov_b64 exec, s[14:15]
	s_bcnt1_i32_b64 s8, s[8:9]
	v_mov_b32_e32 v2, s8
	ds_add_u32 v194, v2

; __device__ __forceinline__ float fast_exp2(float x) { return __builtin_amdgcn_exp2f(x); }
; __device__ __forceinline__ float fast_rcp(float x) { return __builtin_amdgcn_rcpf(x); }
; template <int NB, bool MASK> __device__ __forceinline__ void sb_transform(f32x16* P, float& R, int hi, int kpos0, int qpos) {
;     float T[NB][4];
; #pragma unroll
;     for (int b = 0; b < NB; ++b)
; #pragma unroll
;         for (int g = 0; g < 4; ++g) {
;             float be[4], f[4];
; #pragma unroll
;             for (int i = 0; i < 4; ++i) {
;                 const float z = fmaxf(P[b][4 * g + i], -100.f);
;                 const float e = fast_exp2(-z), rc = fast_rcp(1.f + e);
;                 be[i] = rc; f[i] = e * rc;
;                 if (MASK) { const bool ok = (kpos0 + 32 * b + 8 * g + 4 * hi + i) < qpos; be[i] = ok ? be[i] : 0.f; f[i] = ok ? f[i] : 1.f; }
.LBB0_872:
	s_lshl_b32 s87, s86, 14
	v_add_u32_e32 v2, s87, v211
	v_add_u32_e32 v172, v2, v212
	ds_read_b128 v[176:179], v172 offset:40960
	v_add_u32_e32 v174, v2, v213
	ds_read_b128 v[180:183], v174 offset:40960
	v_add_u32_e32 v175, v2, v214
	s_or_b32 s11, s10, 63
	s_cmp_ge_i32 s11, s78
	s_mov_b64 s[8:9], -1
	s_cselect_b64 s[50:51], -1, 0
	s_cmp_lt_i32 s11, s78
	s_waitcnt lgkmcnt(1)
	v_mfma_f32_32x32x16_bf16 v[84:99], v[176:179], v[100:103], v[68:83]
	v_add_u32_e32 v176, v2, v215
	v_add_u32_e32 v177, v2, v216
	s_waitcnt lgkmcnt(0)
	v_mfma_f32_32x32x16_bf16 v[84:99], v[180:183], v[104:107], v[84:99]
	ds_read_b128 v[178:181], v175 offset:40960
	ds_read_b128 v[182:185], v176 offset:40960
	s_waitcnt lgkmcnt(1)
	v_mfma_f32_32x32x16_bf16 v[84:99], v[178:181], v[108:111], v[84:99]
	v_add_u32_e32 v178, v2, v217
	v_add_u32_e32 v179, v2, v218
	s_waitcnt lgkmcnt(0)
	v_mfma_f32_32x32x16_bf16 v[84:99], v[182:185], v[112:115], v[84:99]
	ds_read_b128 v[180:183], v177 offset:40960
	ds_read_b128 v[184:187], v178 offset:40960
	s_waitcnt lgkmcnt(1)
	v_mfma_f32_32x32x16_bf16 v[84:99], v[180:183], v[116:119], v[84:99]
	v_add_u32_e32 v180, v2, v219
	v_or_b32_e32 v2, s10, v210
	s_waitcnt lgkmcnt(0)
	v_mfma_f32_32x32x16_bf16 v[84:99], v[184:187], v[120:123], v[84:99]
	ds_read_b128 v[182:185], v179 offset:40960
	ds_read_b128 v[186:189], v180 offset:40960
	s_waitcnt lgkmcnt(1)
	v_mfma_f32_32x32x16_bf16 v[84:99], v[182:185], v[124:127], v[84:99]
	s_waitcnt lgkmcnt(0)
	v_mfma_f32_32x32x16_bf16 v[84:99], v[186:189], v[128:131], v[84:99]
	s_nop 11
	v_max_f32_e64 v227, -v84, -v84
	v_max_f32_e64 v226, -v85, -v85
	v_max_f32_e64 v225, -v86, -v86
	v_max_f32_e64 v224, -v87, -v87
	v_max_f32_e64 v223, -v88, -v88
	v_max_f32_e64 v222, -v89, -v89
	v_max_f32_e64 v221, -v90, -v90
	v_max_f32_e64 v189, -v91, -v91
	v_max_f32_e64 v188, -v92, -v92
	v_max_f32_e64 v187, -v93, -v93
	v_max_f32_e64 v186, -v94, -v94
	v_max_f32_e64 v185, -v95, -v95
	v_max_f32_e64 v183, -v96, -v96
	v_max_f32_e64 v184, -v97, -v97
	v_max_f32_e64 v182, -v98, -v98
	v_max_f32_e64 v181, -v99, -v99
	s_cbranch_scc1 .LBB0_874
	v_min_f32_e32 v84, 0x42c80000, v227
	v_exp_f32_e32 v84, v84
	v_min_f32_e32 v85, 0x42c80000, v226
	v_exp_f32_e32 v85, v85
	v_or_b32_e32 v87, 32, v2
	v_add_f32_e32 v86, 1.0, v84
	v_rcp_f32_e32 v86, v86
	v_add_f32_e32 v88, 1.0, v85
	v_rcp_f32_e32 v88, v88
	v_min_f32_e32 v90, 0x42c80000, v224
	v_mul_f32_e32 v89, v84, v86
	v_cmp_lt_i32_e32 vcc, v87, v168
	v_exp_f32_e32 v90, v90
	v_mul_f32_e32 v87, v85, v88
	v_cndmask_b32_e32 v84, 0, v86, vcc
	v_cndmask_b32_e32 v86, 1.0, v89, vcc
	v_or_b32_e32 v89, 33, v2
	v_mov_b32_e32 v85, s45
	v_cmp_lt_i32_e32 vcc, v89, v168
	v_min_f32_e32 v91, 0x42c80000, v223
	v_exp_f32_e32 v93, v91
	v_cndmask_b32_e32 v85, v85, v88, vcc
	v_min_f32_e32 v88, 0x42c80000, v225
	v_exp_f32_e32 v92, v88
	v_add_f32_e32 v88, 1.0, v90
	v_rcp_f32_e32 v89, v88
	v_min_f32_e32 v91, 0x42c80000, v222
	v_exp_f32_e32 v91, v91
	v_cndmask_b32_e32 v88, 1.0, v87, vcc
	v_add_f32_e32 v87, 1.0, v92
	v_rcp_f32_e32 v96, v87
	v_mul_f32_e32 v87, v90, v89
	v_or_b32_e32 v90, 35, v2
	v_cmp_lt_i32_e32 vcc, v90, v168
	v_add_f32_e32 v90, 1.0, v91
	v_rcp_f32_e32 v95, v90
	v_min_f32_e32 v90, 0x42c80000, v221
	v_exp_f32_e32 v90, v90
	v_cndmask_b32_e32 v94, 1.0, v87, vcc
	v_add_f32_e32 v87, 1.0, v93
	v_rcp_f32_e32 v97, v87
	v_add_f32_e32 v98, 1.0, v90
	v_rcp_f32_e32 v99, v98
	v_min_f32_e32 v98, 0x42c80000, v189
	v_exp_f32_e32 v98, v98
	v_mul_f32_e32 v87, v91, v95
	v_or_b32_e32 v91, 41, v2
	v_cmp_lt_i32_e64 s[8:9], v91, v168
	v_min_f32_e32 v91, 0x42c80000, v188
	v_exp_f32_e32 v91, v91
	v_cndmask_b32_e64 v173, 1.0, v87, s[8:9]
	v_mul_f32_e32 v87, v90, v99
	v_add_f32_e32 v90, 1.0, v98
	v_rcp_f32_e32 v231, v90
	v_or_b32_e32 v90, 42, v2
	v_cmp_lt_i32_e64 s[10:11], v90, v168
	v_or_b32_e32 v90, 43, v2
	v_cmp_lt_i32_e64 s[12:13], v90, v168
	v_cndmask_b32_e64 v248, 1.0, v87, s[10:11]
	v_mul_f32_e32 v87, v98, v231
	v_cndmask_b32_e64 v249, 1.0, v87, s[12:13]
	v_min_f32_e32 v87, 0x42c80000, v187
	v_add_f32_e32 v90, 1.0, v91
	v_exp_f32_e32 v87, v87
	v_rcp_f32_e32 v242, v90
	v_or_b32_e32 v90, 48, v2
	v_cmp_lt_i32_e64 s[14:15], v90, v168
	v_add_f32_e32 v98, 1.0, v87
	v_mul_f32_e32 v91, v91, v242
	v_min_f32_e32 v90, 0x42c80000, v185
	v_min_f32_e32 v230, 0x42c80000, v184
	v_rcp_f32_e32 v243, v98
	v_cndmask_b32_e64 v98, 1.0, v91, s[14:15]
	v_exp_f32_e32 v91, v90
	v_exp_f32_e32 v232, v230
	v_min_f32_e32 v90, 0x42c80000, v186
	v_or_b32_e32 v229, 51, v2
	v_exp_f32_e32 v90, v90
	v_add_f32_e32 v228, 1.0, v91
	v_cmp_lt_i32_e64 s[20:21], v229, v168
	v_add_f32_e32 v229, 1.0, v232
	v_rcp_f32_e32 v244, v228
	v_rcp_f32_e32 v245, v229
	v_min_f32_e32 v229, 0x42c80000, v182
	v_or_b32_e32 v170, 49, v2
	v_exp_f32_e32 v233, v229
	v_mul_f32_e32 v87, v87, v243
	v_cmp_lt_i32_e64 s[16:17], v170, v168
	v_pk_mul_f32 v[92:93], v[92:93], v[96:97]
	v_add_f32_e32 v234, 1.0, v233
	v_cndmask_b32_e64 v170, 1.0, v87, s[16:17]
	v_add_f32_e32 v87, 1.0, v90
	v_rcp_f32_e32 v228, v87
	v_mul_f32_e32 v87, v91, v244
	v_min_f32_e32 v91, 0x42c80000, v183
	v_exp_f32_e32 v91, v91
	v_rcp_f32_e32 v246, v234
	v_min_f32_e32 v234, 0x42c80000, v181
	v_exp_f32_e32 v234, v234
	v_cndmask_b32_e64 v230, 1.0, v87, s[20:21]
	v_add_f32_e32 v87, 1.0, v91
	v_rcp_f32_e32 v229, v87
	v_mul_f32_e32 v87, v232, v245
	v_or_b32_e32 v232, 57, v2
	v_cmp_lt_i32_e64 s[26:27], v232, v168
	v_add_f32_e32 v232, 1.0, v234
	v_rcp_f32_e32 v250, v232
	v_or_b32_e32 v232, 58, v2
	v_cndmask_b32_e64 v247, 1.0, v87, s[26:27]
	v_mul_f32_e32 v87, v233, v246
	v_cmp_lt_i32_e64 s[22:23], v232, v168
	v_or_b32_e32 v232, 59, v2
	v_cmp_lt_i32_e64 s[18:19], v232, v168
	v_cndmask_b32_e64 v251, 1.0, v87, s[22:23]
; __device__ __forceinline__ float fast_exp2(float x) { return __builtin_amdgcn_exp2f(x); }
; __device__ __forceinline__ float fast_rcp(float x) { return __builtin_amdgcn_rcpf(x); }
; template <int NB, bool MASK> __device__ __forceinline__ void sb_transform(f32x16* P, float& R, int hi, int kpos0, int qpos) {
;     float T[NB][4];
; #pragma unroll
;     for (int b = 0; b < NB; ++b)
; #pragma unroll
;         for (int g = 0; g < 4; ++g) {
;             float be[4], f[4];
; #pragma unroll
;             for (int i = 0; i < 4; ++i) {
;                 const float z = fmaxf(P[b][4 * g + i], -100.f);
;                 const float e = fast_exp2(-z), rc = fast_rcp(1.f + e);
;                 be[i] = rc; f[i] = e * rc;
;                 if (MASK) { const bool ok = (kpos0 + 32 * b + 8 * g + 4 * hi + i) < qpos; be[i] = ok ? be[i] : 0.f; f[i] = ok ? f[i] : 1.f; }
;             }
;             const float e2 = f[3], e1 = f[2] * f[3], e0 = f[1] * e1;
;             T[b][g] = f[0] * e0;
;             P[b][4 * g + 0] = be[0] * e0; P[b][4 * g + 1] = be[1] * e1; P[b][4 * g + 2] = be[2] * e2; P[b][4 * g + 3] = be[3];
;         }
;     float E = R;
; #pragma unroll
;     for (int b = NB - 1; b >= 0; --b)
; #pragma unroll
;         for (int g = 3; g >= 0; --g) {
;             const float To = __shfl_xor(T[b][g], 32);
;             const float Eg = hi ? E : E * To;
; #pragma unroll
;             for (int i = 0; i < 4; ++i) P[b][4 * g + i] *= Eg;
;             E = E * T[b][g] * To;
;         }
	v_mul_f32_e32 v87, v234, v250
	v_cndmask_b32_e64 v252, 1.0, v87, s[18:19]
	v_xor_b32_e32 v87, 32, v191
	v_add_u32_e32 v232, 64, v192
	v_cmp_lt_i32_e64 s[28:29], v87, v232
	v_or_b32_e32 v232, 50, v2
	v_pk_mul_f32 v[90:91], v[90:91], v[228:229]
	v_cndmask_b32_e64 v87, v191, v87, s[28:29]
	v_lshlrev_b32_e32 v253, 2, v87
	v_or_b32_e32 v87, 56, v2
	v_cmp_lt_i32_e64 s[28:29], v87, v1
	v_or_b32_e32 v87, 34, v2
	v_cmp_lt_i32_e64 s[30:31], v232, v168
	v_cmp_lt_i32_e64 s[34:35], v87, v168
	v_cndmask_b32_e64 v233, 1.0, v91, s[28:29]
	v_cndmask_b32_e64 v232, 1.0, v90, s[30:31]
	v_cndmask_b32_e64 v90, 0, v96, s[34:35]
	v_or_b32_e32 v91, 40, v2
	v_mov_b32_e32 v87, s45
	v_mul_f32_e32 v234, v94, v90
	v_mov_b32_e32 v90, s45
	v_cndmask_b32_e32 v235, v87, v89, vcc
	v_cmp_lt_i32_e32 vcc, v91, v1
	v_cndmask_b32_e64 v90, v90, v99, s[10:11]
	v_mul_f32_e32 v91, v251, v252
	v_cndmask_b32_e64 v241, v87, v231, s[12:13]
	v_mul_f32_e32 v240, v249, v90
	v_mov_b32_e32 v90, s45
	v_mul_f32_e32 v231, v247, v91
	v_cndmask_b32_e64 v236, 1.0, v92, s[34:35]
	v_cndmask_b32_e64 v96, v90, v242, s[14:15]
	v_cndmask_b32_e64 v90, 0, v228, s[30:31]
	v_cndmask_b32_e64 v92, 0, v229, s[28:29]
	v_pk_mul_f32 v[228:229], v[232:233], v[230:231]
	v_mov_b32_e32 v99, v229
	v_mov_b32_e32 v253, v229
	s_nop 1
	v_permlane32_swap_b32_e32 v99, v253
	v_cndmask_b32_e64 v99, v99, v253, s[6:7]
	v_pk_mul_f32 v[232:233], v[170:171], v[228:229]
	v_cndmask_b32_e32 v237, 1.0, v93, vcc
	v_cndmask_b32_e32 v238, 0, v97, vcc
	v_cndmask_b32_e64 v97, v87, v243, s[16:17]
	v_cndmask_b32_e64 v243, v87, v244, s[20:21]
	v_cndmask_b32_e64 v93, v87, v245, s[26:27]
	s_waitcnt lgkmcnt(0)
	v_pk_mul_f32 v[244:245], v[98:99], v[232:233]
	v_mov_b32_e32 v89, v244
	v_mov_b32_e32 v253, v244
	s_nop 1
	v_permlane32_swap_b32_e32 v89, v253
	v_cndmask_b32_e64 v89, v89, v253, s[6:7]
	v_cndmask_b32_e64 v239, v87, v95, s[8:9]
	v_mul_f32_e32 v242, v230, v90
	v_mov_b32_e32 v90, s45
	v_cndmask_b32_e64 v247, v87, v250, s[18:19]
	v_mul_f32_e32 v87, v171, v99
	v_mul_f32_e32 v229, v248, v249
	v_cndmask_b32_e64 v90, v90, v246, s[22:23]
	v_cndmask_b32_e64 v98, v171, v87, s[6:7]
	s_waitcnt lgkmcnt(0)
	v_mul_f32_e32 v87, v245, v89
	v_mul_f32_e32 v95, v173, v229
	v_mul_f32_e32 v246, v252, v90
	v_cndmask_b32_e64 v170, v245, v87, s[6:7]
	v_mul_f32_e32 v87, v244, v245
	v_mov_b32_e32 v90, v231
	v_pk_mul_f32 v[230:231], v[236:237], v[94:95]
	v_mul_f32_e32 v89, v87, v89
	v_mov_b32_e32 v87, v231
	v_mov_b32_e32 v253, v231
	s_nop 1
	v_permlane32_swap_b32_e32 v87, v253
	v_cndmask_b32_e64 v87, v87, v253, s[6:7]
	v_mov_b32_e32 v233, v228
	v_pk_mul_f32 v[96:97], v[232:233], v[96:97]
	v_pk_mul_f32 v[232:233], v[88:89], v[230:231]
	v_mov_b32_e32 v228, v95
	v_pk_mul_f32 v[90:91], v[90:91], v[92:93]
	v_pk_mul_f32 v[94:95], v[228:229], v[238:239]
	s_waitcnt lgkmcnt(0)
	v_pk_mul_f32 v[228:229], v[86:87], v[232:233]
	v_pk_mul_f32 v[90:91], v[90:91], v[98:99] op_sel_hi:[1,0]
	v_pk_mul_f32 v[92:93], v[246:247], v[98:99] op_sel_hi:[1,0]
	v_pk_mul_f32 v[96:97], v[96:97], v[170:171] op_sel_hi:[1,0]
	v_pk_mul_f32 v[98:99], v[242:243], v[170:171] op_sel_hi:[1,0]
	v_mov_b32_e32 v170, v228
	v_mov_b32_e32 v253, v228
	s_nop 1
	v_permlane32_swap_b32_e32 v170, v253
	v_cndmask_b32_e64 v170, v170, v253, s[6:7]
	v_mul_f32_e32 v86, v89, v87
	v_cndmask_b32_e64 v86, v89, v86, s[6:7]
	v_pk_mul_f32 v[88:89], v[94:95], v[86:87] op_sel_hi:[1,0]
	v_mov_b32_e32 v233, v230
	s_waitcnt lgkmcnt(0)
	v_mul_f32_e32 v94, v229, v170
	v_cndmask_b32_e64 v94, v229, v94, s[6:7]
	v_pk_mul_f32 v[84:85], v[232:233], v[84:85]
	v_mul_f32_e32 v173, v228, v229
	v_pk_mul_f32 v[86:87], v[240:241], v[86:87] op_sel_hi:[1,0]
	v_pk_mul_f32 v[84:85], v[84:85], v[94:95] op_sel_hi:[1,0]
	v_pk_mul_f32 v[94:95], v[234:235], v[94:95] op_sel_hi:[1,0]
	v_mul_f32_e32 v173, v173, v170
	s_mov_b64 s[8:9], 0
.LBB0_874:
	s_andn2_b64 vcc, exec, s[8:9]
	s_cbranch_vccnz .LBB0_876
	v_min_f32_e32 v84, 0x42c80000, v227
	v_exp_f32_e32 v85, v84
	v_min_f32_e32 v84, 0x42c80000, v226
	v_exp_f32_e32 v84, v84
	v_min_f32_e32 v86, 0x42c80000, v225
	v_add_f32_e32 v87, 1.0, v85
	v_rcp_f32_e32 v94, v87
	v_min_f32_e32 v87, 0x42c80000, v224
	v_exp_f32_e32 v86, v86
	v_add_f32_e32 v89, 1.0, v84
	v_exp_f32_e32 v224, v87
	v_min_f32_e32 v87, 0x42c80000, v223
	v_rcp_f32_e32 v170, v89
	v_exp_f32_e32 v87, v87
	v_min_f32_e32 v89, 0x42c80000, v222
	v_exp_f32_e32 v89, v89
	v_min_f32_e32 v90, 0x42c80000, v221
	v_mul_f32_e32 v88, v85, v94
	v_add_f32_e32 v85, 1.0, v86
	v_exp_f32_e32 v90, v90
	v_min_f32_e32 v91, 0x42c80000, v189
	v_rcp_f32_e32 v226, v85
	v_add_f32_e32 v85, 1.0, v224
	v_exp_f32_e32 v91, v91
	v_rcp_f32_e32 v222, v85
	v_add_f32_e32 v85, 1.0, v87
	v_rcp_f32_e32 v227, v85
	v_add_f32_e32 v85, 1.0, v89
	v_rcp_f32_e32 v189, v85
	v_add_f32_e32 v85, 1.0, v90
	v_rcp_f32_e32 v228, v85
	v_add_f32_e32 v85, 1.0, v91
	v_rcp_f32_e32 v229, v85
	v_min_f32_e32 v85, 0x42c80000, v188
	v_exp_f32_e32 v85, v85
	v_mul_f32_e32 v225, v89, v189
	v_pk_mul_f32 v[90:91], v[90:91], v[228:229]
	v_pk_mul_f32 v[86:87], v[86:87], v[226:227]
	v_pk_mul_f32 v[230:231], v[90:91], v[90:91] op_sel:[0,1] op_sel_hi:[1,0]
	v_min_f32_e32 v90, 0x42c80000, v186
	v_mul_f32_e32 v228, v228, v91
	v_exp_f32_e32 v90, v90
	v_min_f32_e32 v91, 0x42c80000, v185
	v_exp_f32_e32 v91, v91
	v_add_f32_e32 v89, 1.0, v85
	v_rcp_f32_e32 v96, v89
	v_min_f32_e32 v89, 0x42c80000, v187
	v_exp_f32_e32 v92, v89
	v_add_f32_e32 v89, 1.0, v90
	v_rcp_f32_e32 v98, v89
	v_add_f32_e32 v89, 1.0, v91
	v_rcp_f32_e32 v99, v89
	v_mul_f32_e32 v186, v85, v96
	v_add_f32_e32 v85, 1.0, v92
	v_rcp_f32_e32 v232, v85
	v_pk_mul_f32 v[90:91], v[90:91], v[98:99]
	v_min_f32_e32 v85, 0x42c80000, v184
	v_pk_mul_f32 v[184:185], v[90:91], v[90:91] op_sel:[0,1] op_sel_hi:[1,0]
	v_min_f32_e32 v90, 0x42c80000, v182
	v_exp_f32_e32 v182, v90
	v_min_f32_e32 v90, 0x42c80000, v181
	v_min_f32_e32 v89, 0x42c80000, v183
	v_exp_f32_e32 v183, v90
	v_exp_f32_e32 v85, v85
	v_exp_f32_e32 v234, v89
	v_add_f32_e32 v90, 1.0, v182
	v_rcp_f32_e32 v236, v90
	v_add_f32_e32 v90, 1.0, v183
	v_rcp_f32_e32 v237, v90
	v_add_f32_e32 v89, 1.0, v85
	v_rcp_f32_e32 v89, v89
	v_add_f32_e32 v90, 1.0, v234
	v_rcp_f32_e32 v238, v90
	v_pk_mul_f32 v[182:183], v[182:183], v[236:237]
	v_mul_f32_e32 v235, v85, v89
	v_pk_mul_f32 v[240:241], v[182:183], v[182:183] op_sel:[0,1] op_sel_hi:[1,0]
	v_xor_b32_e32 v85, 32, v191
	v_mov_b32_e32 v239, v240
	v_add_u32_e32 v90, 64, v192
	v_pk_mul_f32 v[234:235], v[234:235], v[238:239]
	v_cmp_lt_i32_e32 vcc, v85, v90
	v_mov_b32_e32 v93, v234
	v_mov_b32_e32 v233, v235
	v_cndmask_b32_e32 v85, v191, v85, vcc
	v_lshlrev_b32_e32 v95, 2, v85
	v_pk_mul_f32 v[92:93], v[92:93], v[232:233]
	v_mov_b32_e32 v187, v93
	v_mov_b32_e32 v95, v93
	s_nop 1
	v_permlane32_swap_b32_e32 v187, v95
	v_cndmask_b32_e64 v187, v187, v95, s[6:7]
	v_mov_b32_e32 v185, v171
	v_mul_f32_e32 v236, v236, v183
	v_pk_mul_f32 v[182:183], v[184:185], v[92:93]
	v_mov_b32_e32 v223, v230
	s_waitcnt lgkmcnt(0)
; #define SBAR() __builtin_amdgcn_sched_barrier(0)
; template <int D0, int KS0> __device__ __forceinline__ void pv_one(f32x16& od, int vb, const bf16x8* pa) {
;     const s16x4 l0 = tr_read<v_rd_off(D0, KS0, 0)>(vb), h0 = tr_read<v_rd_off(D0, KS0, 1)>(vb), l1 = tr_read<v_rd_off(D0, KS0 + 1, 0)>(vb), h1 = tr_read<v_rd_off(D0, KS0 + 1, 1)>(vb);
;     asm volatile("s_waitcnt lgkmcnt(0)" ::: "memory"); SBAR();
;     od = __builtin_amdgcn_mfma_f32_32x32x16_bf16(pa[0], PKV(l0, h0), od, 0, 0, 0);
;     od = __builtin_amdgcn_mfma_f32_32x32x16_bf16(pa[1], PKV(l1, h1), od, 0, 0, 0);
; }
; template <int KS0> __device__ __forceinline__ void pv_blk(f32x16* o, int vb, const bf16x8* pa) {
;     pv_one<0, KS0>(o[0], vb, pa); pv_one<1, KS0>(o[1], vb, pa); pv_one<2, KS0>(o[2], vb, pa); pv_one<3, KS0>(o[3], vb, pa);
; }
; __device__ __forceinline__ void pack_p(const f32x16& P, bf16x8& out0, bf16x8& out1) {
;     ...
;     PK4(0, out0); PK4(8, out1);
;     ...
; }
	v_mul_f32_e32 v85, v171, v187
	v_pk_mul_f32 v[186:187], v[182:183], v[186:187]
	v_cndmask_b32_e64 v92, v171, v85, s[6:7]
	v_mov_b32_e32 v171, v186
	v_mov_b32_e32 v95, v186
	s_nop 1
	v_permlane32_swap_b32_e32 v171, v95
	v_cndmask_b32_e64 v171, v171, v95, s[6:7]
	v_mov_b32_e32 v97, v232
	v_mov_b32_e32 v183, v184
	v_pk_mul_f32 v[184:185], v[224:225], v[222:223]
	v_pk_mul_f32 v[96:97], v[96:97], v[182:183]
	s_waitcnt lgkmcnt(0)
	v_mul_f32_e32 v85, v187, v171
	v_cndmask_b32_e64 v188, v187, v85, s[6:7]
	v_pk_mul_f32 v[182:183], v[186:187], v[186:187] op_sel_hi:[0,1]
	v_pk_mul_f32 v[186:187], v[86:87], v[184:185]
	v_mov_b32_e32 v239, v89
	v_mov_b32_e32 v89, v187
	v_mov_b32_e32 v95, v187
	s_nop 1
	v_permlane32_swap_b32_e32 v89, v95
	v_cndmask_b32_e64 v89, v89, v95, s[6:7]
	v_mov_b32_e32 v85, v183
	v_pk_mul_f32 v[84:85], v[84:85], v[170:171]
	v_mul_f32_e32 v98, v98, v91
	v_pk_mul_f32 v[182:183], v[186:187], v[84:85]
	v_pk_mul_f32 v[96:97], v[96:97], v[188:189] op_sel_hi:[1,0]
	v_pk_mul_f32 v[98:99], v[98:99], v[188:189] op_sel_hi:[1,0]
	v_mul_f32_e32 v224, v226, v184
	v_mov_b32_e32 v188, v227
	s_waitcnt lgkmcnt(0)
	v_pk_mul_f32 v[226:227], v[182:183], v[88:89]
	v_mov_b32_e32 v171, v226
	v_mov_b32_e32 v95, v226
	s_nop 1
	v_permlane32_swap_b32_e32 v171, v95
	v_cndmask_b32_e64 v171, v171, v95, s[6:7]
	v_mul_f32_e32 v84, v85, v89
	v_pk_mov_b32 v[86:87], v[184:185], v[230:231] op_sel:[1,0]
	v_cndmask_b32_e64 v84, v85, v84, s[6:7]
	v_pk_mul_f32 v[86:87], v[188:189], v[86:87]
	v_pk_mov_b32 v[90:91], v[234:235], v[240:241] op_sel:[1,0]
	v_pk_mul_f32 v[88:89], v[86:87], v[84:85] op_sel_hi:[1,0]
	v_pk_mul_f32 v[86:87], v[228:229], v[84:85] op_sel_hi:[1,0]
	s_waitcnt lgkmcnt(0)
	v_mul_f32_e32 v84, v227, v171
	v_mov_b32_e32 v95, v170
	v_mov_b32_e32 v183, v186
	v_pk_mul_f32 v[90:91], v[238:239], v[90:91]
	v_cndmask_b32_e64 v184, v227, v84, s[6:7]
	v_pk_mul_f32 v[84:85], v[94:95], v[182:183]
	v_mov_b32_e32 v225, v222
	v_mul_f32_e32 v170, v226, v227
	v_pk_mul_f32 v[90:91], v[90:91], v[92:93] op_sel_hi:[1,0]
	v_pk_mul_f32 v[92:93], v[236:237], v[92:93] op_sel_hi:[1,0]
	v_pk_mul_f32 v[84:85], v[84:85], v[184:185] op_sel_hi:[1,0]
	v_pk_mul_f32 v[94:95], v[224:225], v[184:185] op_sel_hi:[1,0]
	v_mul_f32_e32 v173, v170, v171
.LBB0_876:
	v_cvt_pk_bf16_f32 v182, v84, v85
	v_cvt_pk_bf16_f32 v183, v94, v95
	v_cvt_pk_bf16_f32 v184, v88, v89
	v_cvt_pk_bf16_f32 v185, v86, v87
	v_cvt_pk_bf16_f32 v234, v96, v97
	v_cvt_pk_bf16_f32 v235, v98, v99
	v_cvt_pk_bf16_f32 v236, v90, v91
	v_cvt_pk_bf16_f32 v237, v92, v93
	s_nop 0
	v_permlane32_swap_b32_e32 v182, v184
	v_permlane32_swap_b32_e32 v183, v185
	v_permlane32_swap_b32_e32 v234, v236
	v_permlane32_swap_b32_e32 v235, v237
	v_add_u32_e32 v170, s87, v220
	ds_read_b64_tr_b16 v[84:85], v170 offset:0x2000
	ds_read_b64_tr_b16 v[86:87], v170 offset:0x2800
	ds_read_b64_tr_b16 v[88:89], v170 offset:0x3000
	ds_read_b64_tr_b16 v[90:91], v170 offset:0x3800
	s_waitcnt lgkmcnt(0)
	s_nop 0
	v_mfma_f32_32x32x16_bf16 v[52:67], v[182:185], v[84:87], v[52:67]
	ds_read_b64_tr_b16 v[84:85], v170 offset:0x2200
	ds_read_b64_tr_b16 v[86:87], v170 offset:0x2a00
	ds_read_b64_tr_b16 v[92:93], v170 offset:0x3200
	ds_read_b64_tr_b16 v[94:95], v170 offset:0x3a00
	s_waitcnt lgkmcnt(0)
	v_mfma_f32_32x32x16_bf16 v[52:67], v[234:237], v[88:91], v[52:67]
	v_mfma_f32_32x32x16_bf16 v[36:51], v[182:185], v[84:87], v[36:51]
	ds_read_b64_tr_b16 v[84:85], v170 offset:0x2400
	ds_read_b64_tr_b16 v[86:87], v170 offset:0x2c00
	ds_read_b64_tr_b16 v[88:89], v170 offset:0x3400
	ds_read_b64_tr_b16 v[90:91], v170 offset:0x3c00
	s_waitcnt lgkmcnt(0)
	v_mfma_f32_32x32x16_bf16 v[36:51], v[234:237], v[92:95], v[36:51]
	v_mfma_f32_32x32x16_bf16 v[20:35], v[182:185], v[84:87], v[20:35]
	ds_read_b64_tr_b16 v[84:85], v170 offset:0x2600
	ds_read_b64_tr_b16 v[86:87], v170 offset:0x2e00
	ds_read_b64_tr_b16 v[238:239], v170 offset:0x3600
	ds_read_b64_tr_b16 v[240:241], v170 offset:0x3e00
	s_waitcnt lgkmcnt(0)
	v_mfma_f32_32x32x16_bf16 v[20:35], v[234:237], v[88:91], v[20:35]
	v_mfma_f32_32x32x16_bf16 v[4:19], v[182:185], v[84:87], v[4:19]
	ds_read_b128 v[182:185], v172 offset:32768
	ds_read_b128 v[186:189], v174 offset:32768
	s_mov_b64 s[8:9], -1
	s_andn2_b64 vcc, exec, s[50:51]
	s_waitcnt lgkmcnt(1)
	v_mfma_f32_32x32x16_bf16 v[84:99], v[182:185], v[100:103], v[68:83]
	s_waitcnt lgkmcnt(0)
	v_mfma_f32_32x32x16_bf16 v[84:99], v[186:189], v[104:107], v[84:99]
	ds_read_b128 v[182:185], v175 offset:32768
	ds_read_b128 v[186:189], v176 offset:32768
	s_waitcnt lgkmcnt(1)
	v_mfma_f32_32x32x16_bf16 v[84:99], v[182:185], v[108:111], v[84:99]
	ds_read_b128 v[174:177], v177 offset:32768
	ds_read_b128 v[182:185], v178 offset:32768
	s_waitcnt lgkmcnt(2)
	v_mfma_f32_32x32x16_bf16 v[84:99], v[186:189], v[112:115], v[84:99]
	s_waitcnt lgkmcnt(1)
	v_mfma_f32_32x32x16_bf16 v[84:99], v[174:177], v[116:119], v[84:99]
	ds_read_b128 v[174:177], v179 offset:32768
	ds_read_b128 v[222:225], v180 offset:32768
	s_waitcnt lgkmcnt(2)
	v_mfma_f32_32x32x16_bf16 v[84:99], v[182:185], v[120:123], v[84:99]
	s_waitcnt lgkmcnt(1)
	v_mfma_f32_32x32x16_bf16 v[84:99], v[174:177], v[124:127], v[84:99]
	s_waitcnt lgkmcnt(0)
	v_mfma_f32_32x32x16_bf16 v[84:99], v[222:225], v[128:131], v[84:99]
	v_mfma_f32_32x32x16_bf16 v[4:19], v[234:237], v[238:241], v[4:19]
	s_nop 10
	v_max_f32_e64 v232, -v84, -v84
	v_max_f32_e64 v231, -v85, -v85
	v_max_f32_e64 v230, -v86, -v86
	v_max_f32_e64 v229, -v87, -v87
	v_max_f32_e64 v228, -v88, -v88
	v_max_f32_e64 v227, -v89, -v89
	v_max_f32_e64 v226, -v90, -v90
	v_max_f32_e64 v225, -v91, -v91
	v_max_f32_e64 v224, -v92, -v92
	v_max_f32_e64 v223, -v93, -v93
	v_max_f32_e64 v222, -v94, -v94
	v_max_f32_e64 v221, -v95, -v95
	v_max_f32_e64 v94, -v96, -v96
	v_max_f32_e64 v95, -v97, -v97
	v_max_f32_e64 v93, -v98, -v98
	v_max_f32_e64 v92, -v99, -v99
	s_cbranch_vccnz .LBB0_878
; __device__ __forceinline__ float fast_exp2(float x) { return __builtin_amdgcn_exp2f(x); }
; __device__ __forceinline__ float fast_rcp(float x) { return __builtin_amdgcn_rcpf(x); }
; template <int NB, bool MASK> __device__ __forceinline__ void sb_transform(f32x16* P, float& R, int hi, int kpos0, int qpos) {
;     float T[NB][4];
; #pragma unroll
;     for (int b = 0; b < NB; ++b)
; #pragma unroll
;         for (int g = 0; g < 4; ++g) {
;             float be[4], f[4];
; #pragma unroll
;             for (int i = 0; i < 4; ++i) {
;                 const float z = fmaxf(P[b][4 * g + i], -100.f);
;                 const float e = fast_exp2(-z), rc = fast_rcp(1.f + e);
;                 be[i] = rc; f[i] = e * rc;
;                 if (MASK) { const bool ok = (kpos0 + 32 * b + 8 * g + 4 * hi + i) < qpos; be[i] = ok ? be[i] : 0.f; f[i] = ok ? f[i] : 1.f; }
;             }
;             const float e2 = f[3], e1 = f[2] * f[3], e0 = f[1] * e1;
;             T[b][g] = f[0] * e0;
;             P[b][4 * g + 0] = be[0] * e0; P[b][4 * g + 1] = be[1] * e1; P[b][4 * g + 2] = be[2] * e2; P[b][4 * g + 3] = be[3];
;         }
;     float E = R;
; #pragma unroll
;     for (int b = NB - 1; b >= 0; --b)
; #pragma unroll
;         for (int g = 3; g >= 0; --g) {
;             const float To = __shfl_xor(T[b][g], 32);
;             const float Eg = hi ? E : E * To;
; #pragma unroll
;             for (int i = 0; i < 4; ++i) P[b][4 * g + i] *= Eg;
;             E = E * T[b][g] * To;
;         }
	v_min_f32_e32 v84, 0x42c80000, v232
	v_exp_f32_e32 v84, v84
	v_min_f32_e32 v85, 0x42c80000, v231
	v_exp_f32_e32 v85, v85
	v_min_f32_e32 v91, 0x42c80000, v228
	v_add_f32_e32 v86, 1.0, v84
	v_rcp_f32_e32 v86, v86
	v_add_f32_e32 v87, 1.0, v85
	v_exp_f32_e32 v97, v91
	v_min_f32_e32 v91, 0x42c80000, v227
	v_rcp_f32_e32 v87, v87
	v_exp_f32_e32 v91, v91
	v_min_f32_e32 v90, 0x42c80000, v229
	v_exp_f32_e32 v90, v90
	v_mul_f32_e32 v88, v84, v86
	v_cmp_lt_i32_e32 vcc, v2, v168
	v_or_b32_e32 v89, 1, v2
	v_add_f32_e32 v99, 1.0, v91
	v_cndmask_b32_e32 v84, 0, v86, vcc
	v_cndmask_b32_e32 v86, 1.0, v88, vcc
	v_mul_f32_e32 v88, v85, v87
	v_mov_b32_e32 v85, s45
	v_cmp_lt_i32_e32 vcc, v89, v168
	v_rcp_f32_e32 v171, v99
	v_min_f32_e32 v99, 0x42c80000, v226
	v_cndmask_b32_e32 v85, v85, v87, vcc
	v_min_f32_e32 v87, 0x42c80000, v230
	v_exp_f32_e32 v96, v87
	v_add_f32_e32 v87, 1.0, v90
	v_exp_f32_e32 v172, v99
	v_rcp_f32_e32 v89, v87
	v_add_f32_e32 v87, 1.0, v96
	v_rcp_f32_e32 v98, v87
	v_add_f32_e32 v174, 1.0, v172
	v_mul_f32_e32 v87, v90, v89
	v_or_b32_e32 v90, 3, v2
	v_rcp_f32_e32 v175, v174
	v_min_f32_e32 v174, 0x42c80000, v225
	v_cndmask_b32_e32 v88, 1.0, v88, vcc
	v_cmp_lt_i32_e32 vcc, v90, v168
	v_exp_f32_e32 v174, v174
	v_min_f32_e32 v180, 0x42c80000, v95
	v_cndmask_b32_e32 v90, 1.0, v87, vcc
	v_add_f32_e32 v87, 1.0, v97
	v_rcp_f32_e32 v99, v87
	v_mul_f32_e32 v87, v91, v171
	v_or_b32_e32 v91, 9, v2
	v_cmp_lt_i32_e64 s[8:9], v91, v168
	v_exp_f32_e32 v182, v180
	v_or_b32_e32 v179, 19, v2
	v_cndmask_b32_e64 v91, 1.0, v87, s[8:9]
	v_mul_f32_e32 v87, v172, v175
	v_add_f32_e32 v172, 1.0, v174
	v_rcp_f32_e32 v181, v172
	v_or_b32_e32 v172, 10, v2
	v_cmp_lt_i32_e64 s[10:11], v172, v168
	v_or_b32_e32 v172, 11, v2
	v_cmp_lt_i32_e64 s[12:13], v172, v168
	v_cndmask_b32_e64 v233, 1.0, v87, s[10:11]
	v_mul_f32_e32 v87, v174, v181
	v_min_f32_e32 v174, 0x42c80000, v224
	v_exp_f32_e32 v174, v174
	v_cndmask_b32_e64 v242, 1.0, v87, s[12:13]
	v_min_f32_e32 v87, 0x42c80000, v223
	v_exp_f32_e32 v87, v87
	v_add_f32_e32 v172, 1.0, v174
	v_rcp_f32_e32 v184, v172
	v_or_b32_e32 v172, 16, v2
	v_cmp_lt_i32_e64 s[14:15], v172, v168
	v_min_f32_e32 v172, 0x42c80000, v221
	v_exp_f32_e32 v177, v172
	v_add_f32_e32 v176, 1.0, v87
	v_rcp_f32_e32 v185, v176
	v_min_f32_e32 v176, 0x42c80000, v222
	v_exp_f32_e32 v176, v176
	v_add_f32_e32 v178, 1.0, v177
	v_cmp_lt_i32_e64 s[20:21], v179, v168
	v_add_f32_e32 v179, 1.0, v182
	v_rcp_f32_e32 v186, v178
	v_rcp_f32_e32 v234, v179
	v_min_f32_e32 v179, 0x42c80000, v93
	v_or_b32_e32 v172, 17, v2
	v_exp_f32_e32 v183, v179
	v_mul_f32_e32 v87, v87, v185
	v_cmp_lt_i32_e64 s[16:17], v172, v168
	v_mul_f32_e32 v174, v174, v184
	v_add_f32_e32 v187, 1.0, v183
	v_cndmask_b32_e64 v172, 1.0, v87, s[16:17]
	v_add_f32_e32 v87, 1.0, v176
	v_rcp_f32_e32 v178, v87
	v_mul_f32_e32 v87, v177, v186
	v_min_f32_e32 v177, 0x42c80000, v94
	v_exp_f32_e32 v177, v177
	v_rcp_f32_e32 v238, v187
	v_min_f32_e32 v187, 0x42c80000, v92
	v_exp_f32_e32 v187, v187
	v_cndmask_b32_e64 v180, 1.0, v87, s[20:21]
	v_add_f32_e32 v87, 1.0, v177
	v_rcp_f32_e32 v179, v87
	v_mul_f32_e32 v87, v182, v234
	v_or_b32_e32 v182, 25, v2
	v_cmp_lt_i32_e64 s[26:27], v182, v168
	v_add_f32_e32 v182, 1.0, v187
	v_rcp_f32_e32 v240, v182
	v_or_b32_e32 v182, 26, v2
	v_cndmask_b32_e64 v236, 1.0, v87, s[26:27]
	v_mul_f32_e32 v87, v183, v238
	v_cmp_lt_i32_e64 s[22:23], v182, v168
	v_or_b32_e32 v182, 27, v2
	v_cmp_lt_i32_e64 s[18:19], v182, v168
	v_cndmask_b32_e64 v235, 1.0, v87, s[22:23]
	v_mul_f32_e32 v87, v187, v240
	v_cndmask_b32_e64 v243, 1.0, v87, s[18:19]
	v_xor_b32_e32 v87, 32, v191
	v_add_u32_e32 v182, 64, v192
	v_cmp_lt_i32_e64 s[28:29], v87, v182
	v_or_b32_e32 v182, 18, v2
	v_cmp_lt_i32_e64 s[30:31], v182, v168
	v_cndmask_b32_e64 v87, v191, v87, s[28:29]
	v_lshlrev_b32_e32 v244, 2, v87
	v_or_b32_e32 v87, 24, v2
	v_or_b32_e32 v182, 8, v2
	v_or_b32_e32 v2, 2, v2
	v_pk_mul_f32 v[176:177], v[176:177], v[178:179]
	v_cmp_lt_i32_e64 s[28:29], v87, v1
	v_cmp_lt_i32_e64 s[34:35], v2, v168
	v_mov_b32_e32 v87, s45
	v_mul_f32_e32 v235, v235, v243
	v_cndmask_b32_e64 v177, 1.0, v177, s[28:29]
	v_cndmask_b32_e64 v176, 1.0, v176, s[30:31]
	v_cndmask_b32_e64 v2, 0, v98, s[34:35]
	v_cndmask_b32_e64 v183, v87, v181, s[12:13]
	v_mul_f32_e32 v181, v236, v235
	v_mul_f32_e32 v188, v90, v2
	v_mov_b32_e32 v2, s45
	v_pk_mul_f32 v[236:237], v[176:177], v[180:181]
	v_cndmask_b32_e64 v2, v2, v175, s[10:11]
	v_mov_b32_e32 v175, v237
	v_mov_b32_e32 v244, v237
	s_nop 1
	v_permlane32_swap_b32_e32 v175, v244
	v_cndmask_b32_e64 v175, v175, v244, s[6:7]
	v_cndmask_b32_e32 v189, v87, v89, vcc
	v_cmp_lt_i32_e32 vcc, v182, v1
	v_mul_f32_e32 v182, v242, v2
	v_mov_b32_e32 v2, s45
	v_cndmask_b32_e64 v184, v2, v184, s[14:15]
	v_cndmask_b32_e64 v2, 0, v178, s[30:31]
	v_cndmask_b32_e64 v187, v87, v186, s[20:21]
	v_mul_f32_e32 v186, v180, v2
	v_mov_b32_e32 v2, s45
	v_cndmask_b32_e64 v174, 1.0, v174, s[14:15]
	v_cndmask_b32_e64 v2, v2, v238, s[22:23]
	v_pk_mul_f32 v[238:239], v[172:173], v[236:237]
	v_cndmask_b32_e64 v185, v87, v185, s[16:17]
	s_waitcnt lgkmcnt(0)
	v_pk_mul_f32 v[176:177], v[174:175], v[238:239]
	v_mov_b32_e32 v89, v176
	v_mov_b32_e32 v244, v176
	s_nop 1
	v_permlane32_swap_b32_e32 v89, v244
	v_cndmask_b32_e64 v89, v89, v244, s[6:7]
	v_cndmask_b32_e64 v178, 0, v179, s[28:29]
	v_cndmask_b32_e64 v179, v87, v234, s[26:27]
	v_mov_b32_e32 v234, v181
	v_mov_b32_e32 v239, v236
	v_pk_mul_f32 v[96:97], v[96:97], v[98:99]
	v_cndmask_b32_e64 v241, v87, v240, s[18:19]
	v_mul_f32_e32 v240, v243, v2
	v_mul_f32_e32 v2, v173, v175
	v_pk_mul_f32 v[174:175], v[234:235], v[178:179]
	v_pk_mul_f32 v[178:179], v[238:239], v[184:185]
	v_mul_f32_e32 v185, v233, v242
	v_cndmask_b32_e32 v97, 1.0, v97, vcc
	v_cndmask_b32_e64 v96, 1.0, v96, s[34:35]
	v_cndmask_b32_e32 v98, 0, v99, vcc
	v_cndmask_b32_e64 v99, v87, v171, s[8:9]
	s_waitcnt lgkmcnt(0)
; __device__ __forceinline__ float fast_exp2(float x) { return __builtin_amdgcn_exp2f(x); }
; __device__ __forceinline__ float fast_rcp(float x) { return __builtin_amdgcn_rcpf(x); }
; template <int NB, bool MASK> __device__ __forceinline__ void sb_transform(f32x16* P, float& R, int hi, int kpos0, int qpos) {
;     float T[NB][4];
; #pragma unroll
;     for (int b = 0; b < NB; ++b)
; #pragma unroll
;         for (int g = 0; g < 4; ++g) {
;             float be[4], f[4];
; #pragma unroll
;             for (int i = 0; i < 4; ++i) {
;                 const float z = fmaxf(P[b][4 * g + i], -100.f);
;                 const float e = fast_exp2(-z), rc = fast_rcp(1.f + e);
;                 be[i] = rc; f[i] = e * rc;
;                 if (MASK) { const bool ok = (kpos0 + 32 * b + 8 * g + 4 * hi + i) < qpos; be[i] = ok ? be[i] : 0.f; f[i] = ok ? f[i] : 1.f; }
;             }
;             const float e2 = f[3], e1 = f[2] * f[3], e0 = f[1] * e1;
;             T[b][g] = f[0] * e0;
;             P[b][4 * g + 0] = be[0] * e0; P[b][4 * g + 1] = be[1] * e1; P[b][4 * g + 2] = be[2] * e2; P[b][4 * g + 3] = be[3];
;         }
;     float E = R;
; #pragma unroll
;     for (int b = NB - 1; b >= 0; --b)
; #pragma unroll
;         for (int g = 3; g >= 0; --g) {
;             const float To = __shfl_xor(T[b][g], 32);
;             const float Eg = hi ? E : E * To;
; #pragma unroll
;             for (int i = 0; i < 4; ++i) P[b][4 * g + i] *= Eg;
;             E = E * T[b][g] * To;
;         }
	v_mul_f32_e32 v87, v177, v89
	v_mul_f32_e32 v91, v91, v185
	v_cndmask_b32_e64 v172, v177, v87, s[6:7]
	v_mul_f32_e32 v87, v176, v177
	v_pk_mul_f32 v[96:97], v[96:97], v[90:91]
	v_mul_f32_e32 v89, v87, v89
	v_mov_b32_e32 v87, v97
	v_mov_b32_e32 v244, v97
	s_nop 1
	v_permlane32_swap_b32_e32 v87, v244
	v_cndmask_b32_e64 v87, v87, v244, s[6:7]
	v_pk_mul_f32 v[180:181], v[186:187], v[172:173] op_sel_hi:[1,0]
	v_pk_mul_f32 v[186:187], v[88:89], v[96:97]
	v_mov_b32_e32 v184, v91
	v_pk_mul_f32 v[90:91], v[184:185], v[98:99]
	s_waitcnt lgkmcnt(0)
	v_pk_mul_f32 v[98:99], v[86:87], v[186:187]
	v_mov_b32_e32 v86, v98
	v_mov_b32_e32 v244, v98
	s_nop 1
	v_permlane32_swap_b32_e32 v86, v244
	v_cndmask_b32_e64 v86, v86, v244, s[6:7]
	v_cndmask_b32_e64 v2, v173, v2, s[6:7]
	v_pk_mul_f32 v[176:177], v[174:175], v[2:3] op_sel_hi:[1,0]
	v_pk_mul_f32 v[174:175], v[240:241], v[2:3] op_sel_hi:[1,0]
	v_mul_f32_e32 v2, v89, v87
	v_cndmask_b32_e64 v2, v89, v2, s[6:7]
	v_pk_mul_f32 v[184:185], v[90:91], v[2:3] op_sel_hi:[1,0]
	v_pk_mul_f32 v[182:183], v[182:183], v[2:3] op_sel_hi:[1,0]
	s_waitcnt lgkmcnt(0)
	v_mul_f32_e32 v2, v99, v86
	v_mov_b32_e32 v187, v96
	v_cndmask_b32_e64 v2, v99, v2, s[6:7]
	v_pk_mul_f32 v[84:85], v[186:187], v[84:85]
	v_pk_mul_f32 v[188:189], v[188:189], v[2:3] op_sel_hi:[1,0]
	v_pk_mul_f32 v[186:187], v[84:85], v[2:3] op_sel_hi:[1,0]
	v_mul_f32_e32 v2, v98, v99
	v_pk_mul_f32 v[178:179], v[178:179], v[172:173] op_sel_hi:[1,0]
	v_mul_f32_e32 v171, v2, v86
	s_mov_b64 s[8:9], 0
.LBB0_878:
	s_andn2_b64 vcc, exec, s[8:9]
	s_cbranch_vccnz .LBB0_880
	v_min_f32_e32 v2, 0x42c80000, v232
	v_exp_f32_e32 v2, v2
	v_min_f32_e32 v84, 0x42c80000, v231
	v_exp_f32_e32 v84, v84
	v_min_f32_e32 v85, 0x42c80000, v230
	v_add_f32_e32 v86, 1.0, v2
	v_rcp_f32_e32 v86, v86
	v_min_f32_e32 v87, 0x42c80000, v229
	v_exp_f32_e32 v88, v85
	v_add_f32_e32 v85, 1.0, v84
	v_exp_f32_e32 v96, v87
	v_rcp_f32_e32 v98, v85
	v_min_f32_e32 v85, 0x42c80000, v228
	v_exp_f32_e32 v89, v85
	v_min_f32_e32 v85, 0x42c80000, v227
	v_exp_f32_e32 v85, v85
	v_min_f32_e32 v87, 0x42c80000, v226
	v_mul_f32_e32 v90, v2, v86
	v_add_f32_e32 v2, 1.0, v88
	v_exp_f32_e32 v174, v87
	v_min_f32_e32 v87, 0x42c80000, v225
	v_rcp_f32_e32 v182, v2
	v_add_f32_e32 v2, 1.0, v96
	v_exp_f32_e32 v175, v87
	v_rcp_f32_e32 v172, v2
	v_add_f32_e32 v2, 1.0, v89
	v_rcp_f32_e32 v183, v2
	v_add_f32_e32 v2, 1.0, v85
	v_rcp_f32_e32 v185, v2
	v_add_f32_e32 v2, 1.0, v174
	v_rcp_f32_e32 v186, v2
	v_add_f32_e32 v2, 1.0, v175
	v_rcp_f32_e32 v187, v2
	v_min_f32_e32 v2, 0x42c80000, v224
	v_exp_f32_e32 v2, v2
	v_mul_f32_e32 v97, v85, v185
	v_pk_mul_f32 v[174:175], v[174:175], v[186:187]
	v_min_f32_e32 v87, 0x42c80000, v222
	v_add_f32_e32 v85, 1.0, v2
	v_rcp_f32_e32 v178, v85
	v_min_f32_e32 v85, 0x42c80000, v223
	v_pk_mul_f32 v[188:189], v[174:175], v[174:175] op_sel:[0,1] op_sel_hi:[1,0]
	v_exp_f32_e32 v174, v87
	v_min_f32_e32 v87, 0x42c80000, v221
	v_exp_f32_e32 v176, v85
	v_mul_f32_e32 v186, v186, v175
	v_exp_f32_e32 v175, v87
	v_min_f32_e32 v87, 0x42c80000, v93
	v_exp_f32_e32 v228, v87
	v_min_f32_e32 v87, 0x42c80000, v92
	v_add_f32_e32 v85, 1.0, v174
	v_mul_f32_e32 v222, v2, v178
	v_add_f32_e32 v2, 1.0, v176
	v_exp_f32_e32 v229, v87
	v_rcp_f32_e32 v180, v85
	v_add_f32_e32 v85, 1.0, v175
	v_rcp_f32_e32 v224, v2
	v_min_f32_e32 v2, 0x42c80000, v95
	v_rcp_f32_e32 v181, v85
	v_exp_f32_e32 v2, v2
	v_min_f32_e32 v85, 0x42c80000, v94
	v_exp_f32_e32 v94, v85
	v_add_f32_e32 v87, 1.0, v228
	v_rcp_f32_e32 v92, v87
	v_add_f32_e32 v87, 1.0, v229
	v_rcp_f32_e32 v93, v87
	v_add_f32_e32 v85, 1.0, v2
	v_rcp_f32_e32 v85, v85
	v_add_f32_e32 v87, 1.0, v94
	v_rcp_f32_e32 v230, v87
	v_pk_mul_f32 v[228:229], v[228:229], v[92:93]
	v_mul_f32_e32 v95, v2, v85
	v_pk_mul_f32 v[232:233], v[228:229], v[228:229] op_sel:[0,1] op_sel_hi:[1,0]
	v_xor_b32_e32 v2, 32, v191
	v_mov_b32_e32 v231, v232
	v_add_u32_e32 v87, 64, v192
	v_pk_mul_f32 v[94:95], v[94:95], v[230:231]
	v_cmp_lt_i32_e32 vcc, v2, v87
	v_mov_b32_e32 v177, v94
	v_mov_b32_e32 v225, v95
	v_cndmask_b32_e32 v2, v191, v2, vcc
	v_lshlrev_b32_e32 v87, 2, v2
	v_pk_mul_f32 v[176:177], v[176:177], v[224:225]
	v_mov_b32_e32 v223, v177
	v_mov_b32_e32 v87, v177
	s_nop 1
	v_permlane32_swap_b32_e32 v223, v87
	v_cndmask_b32_e64 v223, v223, v87, s[6:7]
	v_pk_mul_f32 v[174:175], v[174:175], v[180:181]
	v_mul_f32_e32 v92, v92, v229
	v_pk_mul_f32 v[226:227], v[174:175], v[174:175] op_sel:[0,1] op_sel_hi:[1,0]
	v_mov_b32_e32 v231, v85
	v_mov_b32_e32 v227, v173
	v_pk_mul_f32 v[228:229], v[226:227], v[176:177]
	s_waitcnt lgkmcnt(0)
	v_mul_f32_e32 v2, v173, v223
	v_pk_mul_f32 v[222:223], v[228:229], v[222:223]
	v_mov_b32_e32 v99, v222
	v_mov_b32_e32 v87, v222
	s_nop 1
	v_permlane32_swap_b32_e32 v99, v87
	v_cndmask_b32_e64 v99, v99, v87, s[6:7]
	v_pk_mov_b32 v[94:95], v[94:95], v[232:233] op_sel:[1,0]
	v_cndmask_b32_e64 v2, v173, v2, s[6:7]
	v_pk_mul_f32 v[94:95], v[230:231], v[94:95]
	v_mov_b32_e32 v173, v188
	v_pk_mul_f32 v[176:177], v[94:95], v[2:3] op_sel_hi:[1,0]
	v_pk_mul_f32 v[88:89], v[88:89], v[182:183]
	v_pk_mul_f32 v[94:95], v[96:97], v[172:173]
	v_mul_f32_e32 v180, v180, v175
	v_pk_mul_f32 v[174:175], v[92:93], v[2:3] op_sel_hi:[1,0]
	s_waitcnt lgkmcnt(0)
	v_mul_f32_e32 v2, v223, v99
	v_mov_b32_e32 v179, v224
	v_mov_b32_e32 v229, v226
	v_pk_mul_f32 v[88:89], v[88:89], v[94:95]
	v_cndmask_b32_e64 v2, v223, v2, s[6:7]
	v_pk_mul_f32 v[92:93], v[178:179], v[228:229]
	v_mov_b32_e32 v91, v89
	v_mov_b32_e32 v87, v89
	s_nop 1
	v_permlane32_swap_b32_e32 v91, v87
	v_cndmask_b32_e64 v91, v91, v87, s[6:7]
	v_pk_mul_f32 v[178:179], v[92:93], v[2:3] op_sel_hi:[1,0]
	v_pk_mul_f32 v[92:93], v[222:223], v[222:223] op_sel_hi:[0,1]
	v_mov_b32_e32 v85, v93
	v_pk_mul_f32 v[84:85], v[84:85], v[98:99]
	v_pk_mul_f32 v[180:181], v[180:181], v[2:3] op_sel_hi:[1,0]
	v_pk_mul_f32 v[92:93], v[88:89], v[84:85]
	s_waitcnt lgkmcnt(0)
	v_mul_f32_e32 v2, v85, v91
	v_pk_mul_f32 v[90:91], v[92:93], v[90:91]
	v_mov_b32_e32 v89, v90
	v_mov_b32_e32 v87, v90
	s_nop 1
	v_permlane32_swap_b32_e32 v89, v87
	v_cndmask_b32_e64 v89, v89, v87, s[6:7]
	v_mul_f32_e32 v84, v182, v94
	v_mov_b32_e32 v184, v183
	v_pk_mov_b32 v[94:95], v[94:95], v[188:189] op_sel:[1,0]
	v_cndmask_b32_e64 v2, v85, v2, s[6:7]
	v_pk_mul_f32 v[94:95], v[184:185], v[94:95]
	v_pk_mul_f32 v[182:183], v[186:187], v[2:3] op_sel_hi:[1,0]
	v_pk_mul_f32 v[184:185], v[94:95], v[2:3] op_sel_hi:[1,0]
	s_waitcnt lgkmcnt(0)
	v_mul_f32_e32 v2, v91, v89
	v_mov_b32_e32 v87, v98
	v_mov_b32_e32 v93, v88
	v_cndmask_b32_e64 v2, v91, v2, s[6:7]
	v_pk_mul_f32 v[86:87], v[86:87], v[92:93]
	v_mov_b32_e32 v85, v172
	v_pk_mul_f32 v[186:187], v[86:87], v[2:3] op_sel_hi:[1,0]
	v_pk_mul_f32 v[188:189], v[84:85], v[2:3] op_sel_hi:[1,0]
	v_mul_f32_e32 v2, v90, v91
	v_mul_f32_e32 v171, v2, v89

; #define PSTAMP(i) do { if (PROBE_SEG >= 20 && blockIdx.x == PROBE_BLK && threadIdx.x == 0) ((volatile LAS unsigned long long*)(ctlw + 32))[8 + (i)] = __builtin_amdgcn_s_memrealtime(); } while (0)
; #define GROUP_LOOP(qi, total, ...) for (int gi_ = 0;; ++gi_) { if (threadIdx.x == 0) ctlw[22 + (gi_ & 1)] = __hip_atomic_fetch_add(qbase + 64 * (qi), 1u, __ATOMIC_RELAXED, __HIP_MEMORY_SCOPE_AGENT); \
;         group_bar(gb, lane); const int u = (int)ctlw[22 + (gi_ & 1)]; if (u >= (total)) break; __VA_ARGS__ }
; template <int MASK> __device__ __forceinline__ void phase3(const Params& p, LAS unsigned char* lds, volatile LAS unsigned* ctlw, int qset) {
;     ...
;             PSTAMP(6);
;             GROUP_LOOP(3, U_MEMP + U_MEMS, {
.Lmem_poll_done:
	buffer_inv sc1
	s_waitcnt vmcnt(0)
	s_add_u32 s26, s90, 0xd700000
	s_addc_u32 s27, s91, 0
	s_add_u32 s29, s90, 0xda00000
	s_addc_u32 s30, s91, 0
	s_add_u32 s31, s90, 0xd300000
	s_addc_u32 s34, s91, 0
	s_add_u32 s35, s90, 0xd500000
	s_addc_u32 s44, s91, 0
	s_add_i32 s46, 0, 0x27e50
	s_mov_b32 s7, 0
	s_waitcnt vmcnt(4)
	v_mov_b32_e32 v147, 0
	v_mov_b32_e32 v1, s46
	s_movk_i32 s47, 0x11f
	s_movk_i32 s50, 0x3600
	s_movk_i32 s51, 0x70
	s_mov_b32 s53, 0xfffff0
	s_movk_i32 s54, 0xc0
	s_movk_i32 s55, 0x60
	s_movk_i32 s62, 0x80
	s_movk_i32 s63, 0xa0
	s_movk_i32 s64, 0xe0
	s_movk_i32 s65, 0x118
	s_mov_b64 s[8:9], 0x4000
	s_mov_b64 s[10:11], 0x8000
	s_mov_b64 s[12:13], 0xc000
	s_mov_b64 s[14:15], 0xc00
	s_and_saveexec_b64 s[4:5], s[0:1]
	s_cbranch_execz .Lpf_m0
	v_mov_b32_e32 v255, 1
	global_atomic_add v255, v147, v255, s[90:91] offset:1024 sc0
.Lpf_m0:
	s_or_b64 exec, exec, s[4:5]
	s_mov_b32 s66, 0
	s_branch .LBB0_886

.LBB0_889:
	s_or_b64 exec, exec, s[16:17]
	s_and_b32 s6, s66, 1
	s_lshl_b32 s6, s6, 2
	s_add_i32 s6, s6, 0
	s_waitcnt vmcnt(0)
	v_mov_b32_e32 v3, v255
	s_nop 0
	v_readfirstlane_b32 s16, v3
	s_add_i32 s6, s6, 0x27e58
	v_mov_b32_e32 v3, s6
	v_add_u32_e32 v2, s16, v2
	ds_write_b32 v3, v2

; #define GROUP_LOOP(qi, total, ...) for (int gi_ = 0;; ++gi_) { if (threadIdx.x == 0) ctlw[22 + (gi_ & 1)] = __hip_atomic_fetch_add(qbase + 64 * (qi), 1u, __ATOMIC_RELAXED, __HIP_MEMORY_SCOPE_AGENT); \
;         group_bar(gb, lane); const int u = (int)ctlw[22 + (gi_ & 1)]; if (u >= (total)) break; __VA_ARGS__ }
; template <int MODE> ...
;     ...
;     { int qrow = wid * 32 + r32; qrow = qrow < a.nvalid ? qrow : a.nvalid - 1;
;       const bf16_t* Qw = a.Q + (size_t)qrow * a.qstride + hi * 8;
; #pragma unroll
;       for (int d0 = 0; d0 < 8; ++d0) qr[d0] = *(const bf16x8*)(Qw + d0 * 16); }
; template <int MASK> __device__ __forceinline__ void phase3(const Params& p, LAS unsigned char* lds, volatile LAS unsigned* ctlw, int qset) {
;     ...
;             GROUP_LOOP(3, U_MEMP + U_MEMS, {
;                 if (u < U_MEMP) { const int hm = u & 3, qb = (u >> 2) & 15, b = u >> 6; const size_t r0 = (size_t)(b * SEQ + qb * 128);
;                     attn_unit<1>(lds, gb, PROJ + r0 * NPAD + PC_MQ + hm * 128, NPAD, (const bf16_t*)(p.ws + WS_MKN) + (size_t)(b * MEMT) * 512 + hm * 128, (const bf16_t*)(p.ws + WS_MVB) + (size_t)(b * MEMT) * 512 + hm * 128, 512,
;                                  4, 0, 128, 0.f, PROJ + r0 * NPAD + PC_GM + hm * 128, NPAD, MIX + r0 * 2048 + 1536 + hm * 128, 2048); }
;                 else { const int v = u - U_MEMP, hm = v & 3, sq = v >> 2; const size_t r0 = (size_t)(MP + sq * DTOK);
;                     attn_unit<1>(lds, gb, PROJ + r0 * NPAD + PC_MQ + hm * 128, NPAD, (const bf16_t*)(p.ws + WS_CMK) + (size_t)(sq * MEMT) * 512 + hm * 128, (const bf16_t*)(p.ws + WS_CMV) + (size_t)(sq * MEMT) * 512 + hm * 128, 512,
;                                  4, 0, DTOK, 0.f, PROJ + r0 * NPAD + PC_GM + hm * 128, NPAD, MIX + r0 * 2048 + 1536 + hm * 128, 2048); } })
.LBB0_895:
	s_and_b32 s4, s66, 1
	s_lshl_b32 s4, s4, 2
	s_add_i32 s4, s4, 0
	s_add_i32 s4, s4, 0x27e58
	v_mov_b32_e32 v2, s4
	ds_read_b32 v2, v2
	s_mov_b64 s[4:5], -1
	s_waitcnt lgkmcnt(0)
	v_cmp_lt_i32_e32 vcc, s47, v2
	v_readfirstlane_b32 s20, v2
	s_cbranch_vccnz .LBB0_885
	s_and_saveexec_b64 s[18:19], s[0:1]
	s_cbranch_execz .Lpf_m1
	v_mov_b32_e32 v255, 1
	global_atomic_add v255, v147, v255, s[90:91] offset:1024 sc0
.Lpf_m1:
	s_or_b64 exec, exec, s[18:19]
	s_cmpk_gt_i32 s20, 0xff
	s_cbranch_scc0 .LBB0_919
	s_add_i32 s4, s20, 0xffffff00
	s_lshr_b32 s72, s4, 2
	s_lshl_b32 s4, s72, 3
	s_add_i32 s6, s4, 0x2000
	s_mul_i32 s5, s6, 0x3600
	s_mul_hi_u32 s4, s6, 0x3600
	s_add_u32 s22, s48, s5
	s_addc_u32 s23, s49, s4
	s_lshl_b32 s4, s20, 7
	s_and_b32 s4, s4, 0x180
	s_lshl_b32 s21, s4, 1
	s_add_u32 s4, s22, s21
	s_addc_u32 s5, s23, 0
	s_waitcnt vmcnt(1)
	v_mov_b32_e32 v156, v0
	s_add_u32 s4, s4, 0x2c00
	s_addc_u32 s5, s5, 0
	v_readfirstlane_b32 s71, v156
	s_ashr_i32 s70, s71, 6
	v_and_b32_e32 v157, 31, v156
	s_lshl_b32 s67, s70, 5
	v_or_b32_e32 v2, s67, v157
	v_bfe_u32 v158, v156, 5, 1
	v_min_i32_e32 v4, 7, v2
	v_mov_b64_e32 v[2:3], s[4:5]
	v_mad_i64_i32 v[2:3], s[4:5], v4, s50, v[2:3]
	v_lshlrev_b32_e32 v148, 4, v158
	v_mov_b32_e32 v149, v147
	v_lshl_add_u64 v[2:3], v[2:3], 0, v[148:149]
	global_load_dwordx4 v[82:85], v[2:3], off
	global_load_dwordx4 v[86:89], v[2:3], off offset:32
	global_load_dwordx4 v[90:93], v[2:3], off offset:64
	global_load_dwordx4 v[94:97], v[2:3], off offset:96
	global_load_dwordx4 v[98:101], v[2:3], off offset:128
	global_load_dwordx4 v[102:105], v[2:3], off offset:160
	global_load_dwordx4 v[106:109], v[2:3], off offset:192
	global_load_dwordx4 v[110:113], v[2:3], off offset:224
	s_waitcnt lgkmcnt(0)
	v_and_b32_e32 v149, 63, v156
	v_cmp_eq_u32_e64 s[4:5], 0, v149
	s_and_saveexec_b64 s[16:17], s[4:5]
	s_cbranch_execz .LBB0_900
	s_mov_b64 s[18:19], exec
	v_mbcnt_lo_u32_b32 v2, s18, 0
	v_mbcnt_hi_u32_b32 v2, s19, v2
	v_cmp_eq_u32_e32 vcc, 0, v2
	s_and_b64 s[74:75], exec, vcc
	s_mov_b64 exec, s[74:75]
	s_bcnt1_i32_b64 s18, s[18:19]
	v_mov_b32_e32 v2, s46
	v_mov_b32_e32 v3, s18
	ds_add_u32 v2, v3
